# skinny GEMM units (gateA,gateB,out,up,down): unit index permuted so the 8 (or 2) workgroups sharing one weight slab have equal blockIdx&7 (one XCD L2)
# speedup vs baseline: 1.0304x; 1.0092x over previous
; template <int RT, class Epi>
; __device__ __forceinline__ void skinny_gemm(const bf16* A, size_t lda, const bf16* Bt, int K, int N, const Epi& epi, int wg, int wg_first, int wg_count, int tid, LAS unsigned char* lds) {
;     const int lane = tid & 63, w = tid >> 6, c = lane & 15, g = lane >> 4;
;     constexpr int NRG = 8 / RT;
;     const int nunit = (N / 32) * NRG, ksteps = K / 256;
;     int me = wg - wg_first; if (me < 0 || me >= wg_count) return;
;     for (int s = me; s < nunit; s += wg_count) {
;         const int n0 = 32 * (s / NRG), r0 = (s % NRG) * (16 * RT);
;         f32x4 acc[RT][2];
; #pragma unroll
;         for (int rt = 0; rt < RT; ++rt) { acc[rt][0] = (f32x4){0.f, 0.f, 0.f, 0.f}; acc[rt][1] = (f32x4){0.f, 0.f, 0.f, 0.f}; }
;         const bf16* ap = A + (size_t)(r0 + c) * lda + (size_t)w * (K / 8) + 8 * g;
;         const bf16* bp = Bt + (size_t)(n0 + c) * K + (size_t)w * (K / 8) + 8 * g;
.LBB0_984:
	v_readlane_b32 s8, v254, 25
	v_readlane_b32 s9, v254, 26
	s_andn2_b64 vcc, exec, s[8:9]
	v_mbcnt_lo_u32_b32 v0, -1, 0
	v_mbcnt_hi_u32_b32 v0, -1, v0
	s_nop 0
	v_cndmask_b32_e64 v1, 0, 1, s[8:9]
	v_cmp_ne_u32_e64 s[4:5], 1, v1
	s_cbranch_vccnz .LBB0_989
	v_readlane_b32 s12, v254, 0
	s_add_u32 s8, s6, 0x38700000
	s_addc_u32 s9, s7, 0
	v_or_b32_e32 v1, s12, v0
	v_ashrrev_i32_e32 v2, 6, v1
	v_ashrrev_i32_e32 v3, 31, v2
	v_bfe_u32 v14, v0, 4, 2
	v_lshlrev_b64 v[4:5], 8, v[2:3]
	s_add_u32 s10, s6, 0x2fe05000
	v_and_b32_e32 v26, 15, v0
	v_lshl_add_u64 v[6:7], s[6:7], 0, v[4:5]
	v_lshlrev_b32_e32 v10, 4, v14
	v_lshlrev_b32_e32 v0, 3, v0
	s_addc_u32 s11, s7, 0
	v_lshl_add_u64 v[6:7], v[6:7], 0, v[10:11]
	s_mov_b64 s[6:7], 0x32500000
	v_ashrrev_i32_e32 v27, 2, v1
	v_and_b32_e32 v28, 24, v0
	v_lshlrev_b32_e32 v15, 2, v26
	v_lshl_add_u64 v[8:9], v[6:7], 0, s[6:7]
	v_lshlrev_b32_e32 v2, 14, v2
	v_cmp_gt_i32_e64 s[6:7], 64, v1
	v_lshlrev_b32_e32 v0, 7, v27
	v_lshlrev_b32_e32 v1, 2, v28
	v_lshl_add_u64 v[4:5], s[2:3], 0, v[4:5]
	v_add3_u32 v2, 0, v15, v2
	v_lshlrev_b32_e32 v3, 9, v14
	v_add3_u32 v29, 0, v0, v1
	v_readlane_b32 s2, v254, 13
	v_lshl_add_u64 v[12:13], v[4:5], 0, v[10:11]
	v_add_u32_e32 v30, 0x10000, v29
	v_add_u32_e32 v31, 0x10010, v29
	v_add_u32_e32 v32, 0x14000, v29
	v_add_u32_e32 v33, 0x14010, v29
	v_add_u32_e32 v34, 0x18000, v29
	v_add_u32_e32 v35, 0x18010, v29
	v_add_u32_e32 v36, 0x1c000, v29
	v_add_u32_e32 v37, 0x1c010, v29
	v_add_u32_e32 v38, v2, v3
	s_mov_b32 s12, s2
	v_readlane_b32 s13, v255, 8
	s_mov_b32 s14, s52
	v_readlane_b32 s3, v254, 14
	s_nop 1
	s_cmpk_eq_i32 s90, 0x100
	s_cbranch_scc0 .Lskperm_984
	s_and_b32 s14, s52, 7
	s_lshl_b32 s14, s14, 5
	s_lshr_b32 s12, s52, 6
	s_lshl_b32 s12, s12, 3
	s_add_i32 s14, s14, s12
	s_bfe_u32 s12, s52, 0x30003
	s_add_i32 s14, s14, s12
	s_lshl_b32 s12, s14, 2
	s_lshl_b32 s13, s14, 4
.Lskperm_984:
	s_branch .LBB0_987
.LBB0_986:
	s_or_b64 exec, exec, s[2:3]
	v_readlane_b32 s2, v255, 9
	s_add_i32 s14, s14, s90
	s_add_i32 s13, s13, s41
	s_add_i32 s12, s12, s2
	s_cmpk_lt_i32 s14, 0x100
	s_waitcnt lgkmcnt(0)
	s_barrier
	s_cbranch_scc0 .LBB0_989

; template <int RT, class Epi>
; __device__ __forceinline__ void skinny_gemm(const bf16* A, size_t lda, const bf16* Bt, int K, int N, const Epi& epi, int wg, int wg_first, int wg_count, int tid, LAS unsigned char* lds) {
;     const int lane = tid & 63, w = tid >> 6, c = lane & 15, g = lane >> 4;
;     constexpr int NRG = 8 / RT;
;     const int nunit = (N / 32) * NRG, ksteps = K / 256;
;     int me = wg - wg_first; if (me < 0 || me >= wg_count) return;
;     for (int s = me; s < nunit; s += wg_count) {
;         const int n0 = 32 * (s / NRG), r0 = (s % NRG) * (16 * RT);
;         f32x4 acc[RT][2];
; #pragma unroll
;         for (int rt = 0; rt < RT; ++rt) { acc[rt][0] = (f32x4){0.f, 0.f, 0.f, 0.f}; acc[rt][1] = (f32x4){0.f, 0.f, 0.f, 0.f}; }
;         const bf16* ap = A + (size_t)(r0 + c) * lda + (size_t)w * (K / 8) + 8 * g;
;         const bf16* bp = Bt + (size_t)(n0 + c) * K + (size_t)w * (K / 8) + 8 * g;
.LBB0_1009:
	s_and_b64 vcc, exec, s[4:5]
	v_mbcnt_lo_u32_b32 v0, -1, 0
	v_mbcnt_hi_u32_b32 v0, -1, v0
	s_cbranch_vccnz .LBB0_1016
	s_add_u32 s2, s8, 0x38700000
	v_readlane_b32 s6, v254, 0
	s_addc_u32 s3, s9, 0
	v_and_b32_e32 v26, 15, v0
	v_or_b32_e32 v1, s6, v0
	v_bfe_u32 v4, v0, 4, 2
	v_lshlrev_b32_e32 v0, 3, v0
	s_add_u32 s10, s8, 0x3c800000
	v_ashrrev_i32_e32 v2, 6, v1
	v_ashrrev_i32_e32 v27, 2, v1
	v_and_b32_e32 v28, 24, v0
	s_addc_u32 s11, s9, 0
	v_ashrrev_i32_e32 v3, 31, v2
	v_cmp_gt_i32_e64 s[6:7], 64, v1
	v_lshlrev_b32_e32 v0, 7, v27
	v_lshlrev_b32_e32 v1, 2, v28
	s_add_u32 s12, s8, 0x2fe05800
	v_add3_u32 v29, 0, v0, v1
	v_lshlrev_b64 v[0:1], 9, v[2:3]
	v_readlane_b32 s14, v255, 34
	s_addc_u32 s13, s9, 0
	v_lshl_or_b32 v0, v4, 4, v0
	s_mul_i32 s14, s14, 0x3100000
	v_lshl_add_u64 v[8:9], s[8:9], 0, v[0:1]
	s_add_u32 s8, s8, s14
	v_lshlrev_b32_e32 v5, 2, v26
	v_lshlrev_b32_e32 v6, 14, v2
	s_addc_u32 s9, s9, s97
	v_add3_u32 v5, 0, v5, v6
	v_lshlrev_b32_e32 v6, 9, v4
	v_readlane_b32 s15, v255, 35
	v_lshl_add_u64 v[12:13], s[8:9], 0, v[0:1]
	v_readlane_b32 s8, v254, 13
	v_add_u32_e32 v30, 0x10000, v29
	v_add_u32_e32 v31, 0x10010, v29
	v_add_u32_e32 v32, 0x14000, v29
	v_add_u32_e32 v33, 0x14010, v29
	v_add_u32_e32 v34, 0x18000, v29
	v_add_u32_e32 v35, 0x18010, v29
	v_add_u32_e32 v36, 0x1c000, v29
	v_add_u32_e32 v37, 0x1c010, v29
	v_lshlrev_b32_e32 v38, 11, v26
	v_add_u32_e32 v39, v5, v6
	s_mov_b32 s14, s8
	v_readlane_b32 s15, v255, 8
	s_mov_b32 s16, s52
	v_readlane_b32 s9, v254, 14
	s_nop 1
	s_cmpk_eq_i32 s90, 0x100
	s_cbranch_scc0 .Lskperm_1009
	s_and_b32 s16, s52, 7
	s_lshl_b32 s16, s16, 5
	s_lshr_b32 s14, s52, 6
	s_lshl_b32 s14, s14, 3
	s_add_i32 s16, s16, s14
	s_bfe_u32 s14, s52, 0x30003
	s_add_i32 s16, s16, s14
	s_lshl_b32 s14, s16, 2
	s_lshl_b32 s15, s16, 4
.Lskperm_1009:
	s_branch .LBB0_1012
.LBB0_1011:
	s_or_b64 exec, exec, s[8:9]
	v_readlane_b32 s8, v255, 9
	s_add_i32 s16, s16, s90
	s_add_i32 s15, s15, s41
	s_add_i32 s14, s14, s8
	s_cmpk_lt_i32 s16, 0x100
	s_waitcnt lgkmcnt(0)
	s_barrier
	s_cbranch_scc0 .LBB0_1016

; template <int RT, class Epi>
; __device__ __forceinline__ void skinny_gemm(const bf16* A, size_t lda, const bf16* Bt, int K, int N, const Epi& epi, int wg, int wg_first, int wg_count, int tid, LAS unsigned char* lds) {
;     const int lane = tid & 63, w = tid >> 6, c = lane & 15, g = lane >> 4;
;     constexpr int NRG = 8 / RT;
;     const int nunit = (N / 32) * NRG, ksteps = K / 256;
;     int me = wg - wg_first; if (me < 0 || me >= wg_count) return;
;     for (int s = me; s < nunit; s += wg_count) {
;         const int n0 = 32 * (s / NRG), r0 = (s % NRG) * (16 * RT);
;         f32x4 acc[RT][2];
; #pragma unroll
;         for (int rt = 0; rt < RT; ++rt) { acc[rt][0] = (f32x4){0.f, 0.f, 0.f, 0.f}; acc[rt][1] = (f32x4){0.f, 0.f, 0.f, 0.f}; }
;         const bf16* ap = A + (size_t)(r0 + c) * lda + (size_t)w * (K / 8) + 8 * g;
;         const bf16* bp = Bt + (size_t)(n0 + c) * K + (size_t)w * (K / 8) + 8 * g;
.LBB0_1081:
	s_and_b64 vcc, exec, s[4:5]
	v_mbcnt_lo_u32_b32 v4, -1, 0
	v_mbcnt_hi_u32_b32 v4, -1, v4
	s_cbranch_vccnz .LBB0_1086
	v_readlane_b32 s6, v254, 0
	v_and_b32_e32 v20, 15, v4
	v_bfe_u32 v8, v4, 4, 2
	v_or_b32_e32 v5, s6, v4
	v_ashrrev_i32_e32 v6, 6, v5
	v_ashrrev_i32_e32 v7, 31, v6
	v_lshlrev_b64 v[2:3], 8, v[6:7]
	v_lshlrev_b32_e32 v4, 3, v4
	s_add_u32 s10, s2, 0x13400000
	v_lshl_add_u64 v[0:1], s[2:3], 0, v[2:3]
	v_lshlrev_b32_e32 v10, 4, v8
	v_ashrrev_i32_e32 v21, 2, v5
	v_and_b32_e32 v22, 24, v4
	s_addc_u32 s11, s3, 0
	v_lshlrev_b32_e32 v9, 2, v20
	v_lshl_add_u64 v[0:1], v[0:1], 0, v[10:11]
	s_mov_b64 s[2:3], 0x3c800000
	v_lshlrev_b32_e32 v6, 14, v6
	v_cmp_gt_i32_e64 s[6:7], 64, v5
	v_lshlrev_b32_e32 v4, 7, v21
	v_lshlrev_b32_e32 v5, 2, v22
	s_add_u32 s12, s30, 0xc2000
	v_lshl_add_u64 v[0:1], v[0:1], 0, s[2:3]
	v_lshl_add_u64 v[2:3], s[8:9], 0, v[2:3]
	v_add3_u32 v6, 0, v9, v6
	v_lshlrev_b32_e32 v7, 9, v8
	v_add3_u32 v23, 0, v4, v5
	v_readlane_b32 s2, v254, 13
	s_addc_u32 s13, s31, 0
	v_lshl_add_u64 v[2:3], v[2:3], 0, v[10:11]
	v_add_u32_e32 v24, 0x10000, v23
	v_add_u32_e32 v25, 0x10010, v23
	v_add_u32_e32 v26, 0x14000, v23
	v_add_u32_e32 v27, 0x14010, v23
	v_add_u32_e32 v28, 0x18000, v23
	v_add_u32_e32 v29, 0x18010, v23
	v_add_u32_e32 v30, 0x1c000, v23
	v_add_u32_e32 v31, 0x1c010, v23
	v_add_u32_e32 v32, v6, v7
	s_mov_b32 s8, s2
	v_readlane_b32 s9, v255, 8
	s_mov_b32 s14, s52
	v_readlane_b32 s3, v254, 14
	s_nop 1
	s_cmpk_eq_i32 s90, 0x100
	s_cbranch_scc0 .Lskperm_1081
	s_and_b32 s14, s52, 7
	s_lshl_b32 s14, s14, 5
	s_lshr_b32 s8, s52, 6
	s_lshl_b32 s8, s8, 3
	s_add_i32 s14, s14, s8
	s_bfe_u32 s8, s52, 0x30003
	s_add_i32 s14, s14, s8
	s_lshl_b32 s8, s14, 2
	s_lshl_b32 s9, s14, 4
.Lskperm_1081:
	s_branch .LBB0_1084
.LBB0_1083:
	s_or_b64 exec, exec, s[2:3]
	v_readlane_b32 s2, v255, 9
	s_add_i32 s14, s14, s90
	s_add_i32 s9, s9, s41
	s_add_i32 s8, s8, s2
	s_cmpk_lt_i32 s14, 0x100
	s_waitcnt lgkmcnt(0)
	s_barrier
	s_cbranch_scc0 .LBB0_1086

; template <int RT, class Epi>
; __device__ __forceinline__ void skinny_gemm(const bf16* A, size_t lda, const bf16* Bt, int K, int N, const Epi& epi, int wg, int wg_first, int wg_count, int tid, LAS unsigned char* lds) {
;     const int lane = tid & 63, w = tid >> 6, c = lane & 15, g = lane >> 4;
;     constexpr int NRG = 8 / RT;
;     const int nunit = (N / 32) * NRG, ksteps = K / 256;
;     int me = wg - wg_first; if (me < 0 || me >= wg_count) return;
;     for (int s = me; s < nunit; s += wg_count) {
;         const int n0 = 32 * (s / NRG), r0 = (s % NRG) * (16 * RT);
;         f32x4 acc[RT][2];
; #pragma unroll
;         for (int rt = 0; rt < RT; ++rt) { acc[rt][0] = (f32x4){0.f, 0.f, 0.f, 0.f}; acc[rt][1] = (f32x4){0.f, 0.f, 0.f, 0.f}; }
;         const bf16* ap = A + (size_t)(r0 + c) * lda + (size_t)w * (K / 8) + 8 * g;
;         const bf16* bp = Bt + (size_t)(n0 + c) * K + (size_t)w * (K / 8) + 8 * g;
.LBB0_1201:
	s_and_b64 vcc, exec, s[4:5]
	v_mbcnt_lo_u32_b32 v4, -1, 0
	v_mbcnt_hi_u32_b32 v4, -1, v4
	s_cbranch_vccnz .LBB0_1206
	v_readlane_b32 s6, v254, 0
	v_bfe_u32 v8, v4, 4, 2
	v_and_b32_e32 v18, 15, v4
	v_or_b32_e32 v5, s6, v4
	v_ashrrev_i32_e32 v6, 6, v5
	v_ashrrev_i32_e32 v7, 31, v6
	v_lshlrev_b64 v[2:3], 8, v[6:7]
	v_lshl_add_u64 v[0:1], s[8:9], 0, v[2:3]
	v_lshlrev_b32_e32 v10, 4, v8
	v_lshlrev_b32_e32 v4, 3, v4
	v_lshl_add_u64 v[0:1], v[0:1], 0, v[10:11]
	s_mov_b64 s[6:7], 0x17500000
	v_lshl_add_u64 v[2:3], s[2:3], 0, v[2:3]
	s_movk_i32 s2, 0x100
	v_ashrrev_i32_e32 v19, 2, v5
	v_and_b32_e32 v20, 24, v4
	v_lshlrev_b32_e32 v9, 2, v18
	v_lshl_add_u64 v[0:1], v[0:1], 0, s[6:7]
	v_lshlrev_b32_e32 v6, 14, v6
	v_cmp_gt_i32_e64 s[6:7], s2, v5
	v_lshlrev_b32_e32 v4, 7, v19
	v_lshlrev_b32_e32 v5, 2, v20
	s_add_u32 s10, s8, 0x44900000
	v_lshlrev_b32_e32 v7, 9, v8
	v_add3_u32 v6, 0, v9, v6
	v_add3_u32 v21, 0, v4, v5
	s_addc_u32 s11, s9, 0
	v_lshl_add_u64 v[2:3], v[2:3], 0, v[10:11]
	v_add_u32_e32 v22, 0x10000, v21
	v_add_u32_e32 v23, 0x10010, v21
	v_add_u32_e32 v24, 0x14000, v21
	v_add_u32_e32 v25, 0x14010, v21
	v_add_u32_e32 v26, 0x18000, v21
	v_add_u32_e32 v27, 0x18010, v21
	v_add_u32_e32 v28, 0x1c000, v21
	v_add_u32_e32 v29, 0x1c010, v21
	v_add_u32_e32 v30, v6, v7
	v_readlane_b32 s8, v255, 8
	v_readlane_b32 s9, v255, 10
	s_mov_b32 s12, s52
	s_nop 1
	s_cmpk_eq_i32 s90, 0x100
	s_cbranch_scc0 .Lskperm_1201
	s_and_b32 s12, s52, 7
	s_lshl_b32 s12, s12, 5
	s_lshr_b32 s9, s52, 4
	s_lshl_b32 s9, s9, 1
	s_add_i32 s12, s12, s9
	s_bfe_u32 s9, s52, 0x10003
	s_add_i32 s12, s12, s9
	s_lshl_b32 s9, s12, 6
	s_lshl_b32 s8, s12, 4
.Lskperm_1201:
	s_branch .LBB0_1204
.LBB0_1203:
	s_or_b64 exec, exec, s[2:3]
	v_readlane_b32 s2, v255, 11
	s_add_i32 s12, s12, s90
	s_add_i32 s9, s9, s2
	s_add_i32 s8, s8, s41
	s_cmpk_lt_i32 s12, 0x100
	s_waitcnt lgkmcnt(0)
	s_barrier
	s_cbranch_scc0 .LBB0_1206

; template <int RT, class Epi>
; __device__ __forceinline__ void skinny_gemm(const bf16* A, size_t lda, const bf16* Bt, int K, int N, const Epi& epi, int wg, int wg_first, int wg_count, int tid, LAS unsigned char* lds) {
;     const int lane = tid & 63, w = tid >> 6, c = lane & 15, g = lane >> 4;
;     constexpr int NRG = 8 / RT;
;     const int nunit = (N / 32) * NRG, ksteps = K / 256;
;     int me = wg - wg_first; if (me < 0 || me >= wg_count) return;
;     for (int s = me; s < nunit; s += wg_count) {
;         const int n0 = 32 * (s / NRG), r0 = (s % NRG) * (16 * RT);
;         f32x4 acc[RT][2];
; #pragma unroll
;         for (int rt = 0; rt < RT; ++rt) { acc[rt][0] = (f32x4){0.f, 0.f, 0.f, 0.f}; acc[rt][1] = (f32x4){0.f, 0.f, 0.f, 0.f}; }
;         const bf16* ap = A + (size_t)(r0 + c) * lda + (size_t)w * (K / 8) + 8 * g;
;         const bf16* bp = Bt + (size_t)(n0 + c) * K + (size_t)w * (K / 8) + 8 * g;
.LBB0_1271:
	s_and_b64 vcc, exec, s[4:5]
	v_mbcnt_lo_u32_b32 v0, -1, 0
	v_mbcnt_hi_u32_b32 v0, -1, v0
	s_cbranch_vccnz .LBB0_1278
	v_readlane_b32 s0, v254, 0
	v_and_b32_e32 v20, 15, v0
	v_bfe_u32 v4, v0, 4, 2
	v_or_b32_e32 v1, s0, v0
	v_lshlrev_b32_e32 v0, 3, v0
	s_add_u32 s4, s2, 0x13400000
	v_ashrrev_i32_e32 v2, 6, v1
	v_ashrrev_i32_e32 v21, 2, v1
	v_and_b32_e32 v22, 24, v0
	s_addc_u32 s5, s3, 0
	v_ashrrev_i32_e32 v3, 31, v2
	v_cmp_gt_i32_e64 s[0:1], 64, v1
	v_lshlrev_b32_e32 v0, 7, v21
	v_lshlrev_b32_e32 v1, 2, v22
	s_add_u32 s6, s26, 0xc5000
	v_add3_u32 v23, 0, v0, v1
	v_lshlrev_b64 v[0:1], 10, v[2:3]
	s_addc_u32 s7, s27, 0
	v_lshl_or_b32 v0, v4, 4, v0
	v_readlane_b32 s8, v255, 36
	v_lshl_add_u64 v[8:9], s[2:3], 0, v[0:1]
	s_add_u32 s2, s2, s8
	v_lshlrev_b32_e32 v5, 2, v20
	v_lshlrev_b32_e32 v6, 14, v2
	s_addc_u32 s3, s3, s97
	v_add3_u32 v5, 0, v5, v6
	v_lshlrev_b32_e32 v6, 9, v4
	v_lshl_add_u64 v[12:13], s[2:3], 0, v[0:1]
	v_readlane_b32 s2, v254, 13
	v_add_u32_e32 v24, 0x10000, v23
	v_add_u32_e32 v25, 0x10010, v23
	v_add_u32_e32 v26, 0x14000, v23
	v_add_u32_e32 v27, 0x14010, v23
	v_add_u32_e32 v28, 0x18000, v23
	v_add_u32_e32 v29, 0x18010, v23
	v_add_u32_e32 v30, 0x1c000, v23
	v_add_u32_e32 v31, 0x1c010, v23
	v_lshlrev_b32_e32 v32, 12, v20
	v_add_u32_e32 v33, v5, v6
	s_mov_b32 s8, s2
	v_readlane_b32 s9, v255, 8
	s_mov_b32 s10, s52
	v_readlane_b32 s3, v254, 14
	s_nop 1
	s_cmpk_eq_i32 s90, 0x100
	s_cbranch_scc0 .Lskperm_1271
	s_and_b32 s10, s52, 7
	s_lshl_b32 s10, s10, 5
	s_lshr_b32 s8, s52, 6
	s_lshl_b32 s8, s8, 3
	s_add_i32 s10, s10, s8
	s_bfe_u32 s8, s52, 0x30003
	s_add_i32 s10, s10, s8
	s_lshl_b32 s8, s10, 2
	s_lshl_b32 s9, s10, 4
.Lskperm_1271:
	s_branch .LBB0_1274
.LBB0_1273:
	s_or_b64 exec, exec, s[2:3]
	v_readlane_b32 s2, v255, 9
	s_add_i32 s10, s10, s90
	s_add_i32 s9, s9, s41
	s_add_i32 s8, s8, s2
	s_cmpk_lt_i32 s10, 0x100
	s_waitcnt lgkmcnt(0)
	s_barrier
	s_cbranch_scc0 .LBB0_1278
